# f28 + fp8 gate GEMM epilogue: the 8 row-scale and 16 bias loads issued at the unit header before the K-loop (registers the loop does not use); the epilogue no longer loads and drains vmcnt(0) at its s
# speedup vs baseline: 1.0034x; 1.0034x over previous
;     __device__ __forceinline__ bool next(int i, Unit& u) const { const int t = i / 3; const long L = (long)t * G + c; if (L >= tm.nwg) return false; tm.map((int)L, u.pm, u.pn); u.sub = i - 3 * t; return true; }
;     __device__ __forceinline__ bool next(int i, Unit& u) const { const long L = (long)i * G + c; if (L >= tm.nwg) return false; tm.map((int)L, u.pm, u.pn); u.pn += pn0; u.sub = i; return true; }
;     __device__ __forceinline__ void operator()(const Acc& acc, const Unit& u, int wr, int wc, int fr, int fq) const {
;     ...
;         f32x4 bv[2][2];
; #pragma unroll
;         for (int bj = 0; bj < 2; ++bj)
; #pragma unroll
;             for (int n = 0; n < 2; ++n) bv[bj][n] = *(const f32x4*)(b_gate + colt + bj * HALF + 4 * n);
;         float rsv[2][4];
; #pragma unroll
;         for (int ai = 0; ai < 2; ++ai)
; #pragma unroll
;             for (int m = 0; m < 4; ++m) rsv[ai][m] = rinvx[row0 + ai * HALF + m * 16] * (1.0f / 512.0f);
.LBB0_564:
	v_lshl_add_u32 v4, s42, 8, v193
	v_lshl_or_b32 v6, s0, 8, v189
	v_ashrrev_i32_e32 v5, 31, v4
	v_ashrrev_i32_e32 v7, 31, v6
	v_lshl_add_u64 v[6:7], v[6:7], 2, s[44:45]
	v_lshl_add_u64 v[4:5], v[4:5], 2, s[20:21]
	global_load_dwordx4 v[230:233], v[6:7], off
	global_load_dwordx4 v[234:237], v[6:7], off offset:16
	global_load_dwordx4 v[238:241], v[6:7], off offset:512
	global_load_dwordx4 v[242:245], v[6:7], off offset:528
	global_load_dword v246, v[4:5], off
	global_load_dword v247, v[4:5], off offset:64
	global_load_dword v248, v[4:5], off offset:128
	global_load_dword v249, v[4:5], off offset:192
	global_load_dword v250, v[4:5], off offset:512
	global_load_dword v251, v[4:5], off offset:576
	global_load_dword v195, v[4:5], off offset:640
	global_load_dword v170, v[4:5], off offset:704
	s_add_i32 s25, s25, 1
	s_mul_i32 s1, s25, s15
	s_mul_hi_u32 s4, s25, s14
	s_add_i32 s4, s4, s1
	s_mul_i32 s1, s25, s14
	s_add_u32 s38, s1, s2
	s_addc_u32 s39, s4, s79
	v_cmp_gt_i64_e32 vcc, s[38:39], v[178:179]
	v_cmp_lt_i64_e64 s[4:5], s[38:39], v[176:177]
	s_cbranch_vccnz .LBB0_566
	s_ashr_i32 s1, s38, 31
	s_lshr_b32 s1, s1, 29
	s_add_i32 s1, s38, s1
	s_ashr_i32 s26, s1, 3
	s_and_b32 s1, s1, -8
	s_sub_i32 s1, s38, s1
	s_cmp_lt_i32 s1, 0
	s_cselect_b32 s27, s59, 0x60
	s_mul_i32 s1, s1, s27
	s_add_i32 s1, s1, s26
	s_mul_hi_i32 s26, s1, 0x38e38e39
	s_lshr_b32 s27, s26, 31
	s_ashr_i32 s26, s26, 4
	s_add_i32 s26, s26, s27
	s_mul_i32 s27, s26, 3
	s_sub_i32 s36, 32, s27
	s_min_i32 s36, s36, 3
	s_abs_i32 s37, s36
	v_cvt_f32_u32_e32 v2, s37
	s_sub_i32 s39, 0, s37
	s_mulk_i32 s26, 0x48
	s_sub_i32 s1, s1, s26
	v_rcp_iflag_f32_e32 v2, v2
	s_abs_i32 s26, s1
	s_xor_b32 s38, s1, s36
	s_ashr_i32 s38, s38, 31
	v_mul_f32_e32 v2, 0x4f7ffffe, v2
	v_cvt_u32_f32_e32 v2, v2
	s_nop 0
	v_readfirstlane_b32 s40, v2
	s_mul_i32 s39, s39, s40
	s_mul_hi_u32 s39, s40, s39
	s_add_i32 s40, s40, s39
	s_mul_hi_u32 s39, s26, s40
	s_mul_i32 s40, s39, s37
	s_sub_i32 s26, s26, s40
	s_add_i32 s41, s39, 1
	s_sub_i32 s40, s26, s37
	s_cmp_ge_u32 s26, s37
	s_cselect_b32 s39, s41, s39
	s_cselect_b32 s26, s40, s26
	s_add_i32 s40, s39, 1
	s_cmp_ge_u32 s26, s37
	s_cselect_b32 s26, s40, s39
	s_xor_b32 s26, s26, s38
	s_sub_i32 s26, s26, s38
	s_mul_i32 s36, s26, s36
	s_sub_i32 s1, s1, s36
	s_add_i32 s36, s27, s1

; __device__ __forceinline__ float sigmoidf_(float x) { return frcp(1.0f + fexp(-x)); }
;     __device__ __forceinline__ void operator()(const Acc& acc, const Unit& u, int wr, int wc, int fr, int fq) const {
;     ...
; #pragma unroll
;         for (int ai = 0; ai < 2; ++ai)
; #pragma unroll
;             for (int m = 0; m < 4; ++m) { const int row = row0 + ai * HALF + m * 16; const float rs = rsv[ai][m]; unsigned char* rowp = GT + (size_t)row * NGT + colt;
; #pragma unroll
;                 for (int bj = 0; bj < 2; ++bj) { f32x4 v0 = acc[ai][bj][m][0] * rs + bv[bj][0], v1 = acc[ai][bj][m][1] * rs + bv[bj][1];
;                     unsigned q0[4], q1[4];
; #pragma unroll
;                     for (int e = 0; e < 4; ++e) { q0[e] = (unsigned)fmaxf(sigmoidf_(v0[e]) * 255.0f + 0.5f, 1.0f); q1[e] = (unsigned)fmaxf(sigmoidf_(v1[e]) * 255.0f + 0.5f, 1.0f); }
;                     u32x2 w; w.x = q0[0] | (q0[1] << 8) | (q0[2] << 16) | (q0[3] << 24); w.y = q1[0] | (q1[1] << 8) | (q1[2] << 16) | (q1[3] << 24);
;                     *(u32x2*)(rowp + bj * HALF) = w; } }
; template <class Epi, class Sched, bool ALIGN_EPI, bool SP2>
; __device__ __forceinline__ void gemm_phase8(LAS unsigned char* lds, const int K, const Sched& S, const Epi& E) {
;     ...
;         asm volatile("s_nop 15\n\ts_nop 7" ::: "memory");
.LBB0_570:
	s_nop 15
	s_nop 7
	v_lshl_add_u32 v24, s42, 8, v193
	s_lshl_b32 s1, s0, 8
	v_or_b32_e32 v22, 16, v24
	v_or_b32_e32 v20, 32, v24
	v_or_b32_e32 v18, 48, v24
	s_mov_b64 s[42:43], -1
	s_cmp_lt_i32 s0, 24
	v_ashrrev_i32_e32 v25, 31, v24
	v_add_u32_e32 v183, 0x80, v24
	v_add_u32_e32 v182, 0x90, v24
	v_add_u32_e32 v181, 0xa0, v24
	v_add_u32_e32 v180, 0xb0, v24
	v_ashrrev_i32_e32 v23, 31, v22
	v_ashrrev_i32_e32 v21, 31, v20
	v_ashrrev_i32_e32 v19, 31, v18
	s_cbranch_scc0 .LBB0_573
	v_or_b32_e32 v26, s1, v189
	v_ashrrev_i32_e32 v27, 31, v26
	v_mov_b64_e32 v[28:29], s[88:89]
	v_mad_i64_i32 v[30:31], s[42:43], v24, s62, v[28:29]
	v_lshl_add_u64 v[186:187], v[30:31], 0, v[26:27]
	s_mov_b32 s98, 0x3b808081
	v_mul_f32_e32 v2, 0xbfb8aa3b, v242
	v_mul_f32_e32 v3, 0xbfb8aa3b, v243
	v_mul_f32_e32 v4, 0xbfb8aa3b, v244
	v_mul_f32_e32 v5, 0xbfb8aa3b, v245
	v_mul_f32_e32 v6, 0xbfb8aa3b, v238
	v_mul_f32_e32 v7, 0xbfb8aa3b, v239
	v_mul_f32_e32 v8, 0xbfb8aa3b, v240
	v_mul_f32_e32 v9, 0xbfb8aa3b, v241
	v_mul_f32_e32 v10, 0xbfb8aa3b, v234
	v_mul_f32_e32 v11, 0xbfb8aa3b, v235
	v_mul_f32_e32 v12, 0xbfb8aa3b, v236
	v_mul_f32_e32 v13, 0xbfb8aa3b, v237
	v_mul_f32_e32 v14, 0xbfb8aa3b, v230
	v_mul_f32_e32 v15, 0xbfb8aa3b, v231
	v_mul_f32_e32 v16, 0xbfb8aa3b, v232
	v_mul_f32_e32 v17, 0xbfb8aa3b, v233
	v_mul_f32_e32 v30, 0xbb38aa3b, v170
	v_mul_f32_e32 v199, 0xbb38aa3b, v246
	v_mul_f32_e32 v200, 0xbb38aa3b, v247
	v_mul_f32_e32 v184, 0xbb38aa3b, v248
	v_mul_f32_e32 v170, 0xbb38aa3b, v249
	v_mul_f32_e32 v33, 0xbb38aa3b, v250
	v_mul_f32_e32 v32, 0xbb38aa3b, v251
	v_mul_f32_e32 v31, 0xbb38aa3b, v195
	v_fma_f32 v202, v158, v199, v14
	v_fma_f32 v203, v154, v199, v10
	v_fma_f32 v204, v159, v199, v15
	v_fma_f32 v205, v155, v199, v11
	v_fma_f32 v206, v160, v199, v16
	v_fma_f32 v207, v156, v199, v12
	v_fma_f32 v208, v161, v199, v17
	v_fma_f32 v209, v157, v199, v13
	v_exp_f32_e32 v202, v202
	v_exp_f32_e32 v203, v203
	v_exp_f32_e32 v204, v204
	v_exp_f32_e32 v205, v205
	v_exp_f32_e32 v206, v206
	v_exp_f32_e32 v207, v207
	v_exp_f32_e32 v208, v208
	v_exp_f32_e32 v209, v209
	s_nop 0
	v_fma_f32 v202, v202, s98, s98 clamp
	v_fma_f32 v203, v203, s98, s98 clamp
	v_fma_f32 v204, v204, s98, s98 clamp
	v_fma_f32 v205, v205, s98, s98 clamp
	v_fma_f32 v206, v206, s98, s98 clamp
	v_fma_f32 v207, v207, s98, s98 clamp
	v_fma_f32 v208, v208, s98, s98 clamp
	v_fma_f32 v209, v209, s98, s98 clamp
	v_rcp_f32_e32 v202, v202
	v_rcp_f32_e32 v203, v203
	v_rcp_f32_e32 v204, v204
	v_rcp_f32_e32 v205, v205
	v_rcp_f32_e32 v206, v206
	v_rcp_f32_e32 v207, v207
	v_rcp_f32_e32 v208, v208
	v_rcp_f32_e32 v209, v209
	s_nop 0
	v_cvt_pk_u8_f32 v210, v202, 0, 0
	v_cvt_pk_u8_f32 v210, v204, 1, v210
	v_cvt_pk_u8_f32 v210, v206, 2, v210
	v_cvt_pk_u8_f32 v210, v208, 3, v210
	v_cvt_pk_u8_f32 v211, v203, 0, 0
	v_cvt_pk_u8_f32 v211, v205, 1, v211
	v_cvt_pk_u8_f32 v211, v207, 2, v211
	v_cvt_pk_u8_f32 v211, v209, 3, v211
	global_store_dwordx2 v[186:187], v[210:211], off
	v_fma_f32 v202, v150, v199, v6
	v_fma_f32 v203, v146, v199, v2
	v_fma_f32 v204, v151, v199, v7
	v_fma_f32 v205, v147, v199, v3
	v_fma_f32 v206, v152, v199, v8
	v_fma_f32 v207, v148, v199, v4
	v_fma_f32 v208, v153, v199, v9
	v_fma_f32 v209, v149, v199, v5
	v_exp_f32_e32 v202, v202
	v_exp_f32_e32 v203, v203
	v_exp_f32_e32 v204, v204
	v_exp_f32_e32 v205, v205
	v_exp_f32_e32 v206, v206
	v_exp_f32_e32 v207, v207
	v_exp_f32_e32 v208, v208
	v_exp_f32_e32 v209, v209
	s_nop 0
	v_fma_f32 v202, v202, s98, s98 clamp
	v_fma_f32 v203, v203, s98, s98 clamp
	v_fma_f32 v204, v204, s98, s98 clamp
	v_fma_f32 v205, v205, s98, s98 clamp
	v_fma_f32 v206, v206, s98, s98 clamp
	v_fma_f32 v207, v207, s98, s98 clamp
	v_fma_f32 v208, v208, s98, s98 clamp
	v_fma_f32 v209, v209, s98, s98 clamp
	v_rcp_f32_e32 v202, v202
	v_rcp_f32_e32 v203, v203
	v_rcp_f32_e32 v204, v204
	v_rcp_f32_e32 v205, v205
	v_rcp_f32_e32 v206, v206
	v_rcp_f32_e32 v207, v207
	v_rcp_f32_e32 v208, v208
	v_rcp_f32_e32 v209, v209
	s_nop 0
	v_cvt_pk_u8_f32 v212, v202, 0, 0
	v_cvt_pk_u8_f32 v212, v204, 1, v212
	v_cvt_pk_u8_f32 v212, v206, 2, v212
	v_cvt_pk_u8_f32 v212, v208, 3, v212
	v_cvt_pk_u8_f32 v213, v203, 0, 0
	v_cvt_pk_u8_f32 v213, v205, 1, v213
	v_cvt_pk_u8_f32 v213, v207, 2, v213
	v_cvt_pk_u8_f32 v213, v209, 3, v213
	global_store_dwordx2 v[186:187], v[212:213], off offset:128
	v_fma_f32 v202, v142, v200, v14
	v_fma_f32 v203, v143, v200, v15
	v_fma_f32 v204, v138, v200, v10
	v_fma_f32 v205, v139, v200, v11
	v_fma_f32 v206, v144, v200, v16
	v_fma_f32 v207, v145, v200, v17
	v_fma_f32 v208, v140, v200, v12
	v_fma_f32 v209, v141, v200, v13
	v_exp_f32_e32 v202, v202
	v_exp_f32_e32 v203, v203
	v_exp_f32_e32 v204, v204
	v_exp_f32_e32 v205, v205
	v_exp_f32_e32 v206, v206
	v_exp_f32_e32 v207, v207
	v_exp_f32_e32 v208, v208
	v_exp_f32_e32 v209, v209
	s_nop 0
	v_fma_f32 v202, v202, s98, s98 clamp
	v_fma_f32 v203, v203, s98, s98 clamp
	v_fma_f32 v204, v204, s98, s98 clamp
	v_fma_f32 v205, v205, s98, s98 clamp
	v_fma_f32 v206, v206, s98, s98 clamp
	v_fma_f32 v207, v207, s98, s98 clamp
	v_fma_f32 v208, v208, s98, s98 clamp
	v_fma_f32 v209, v209, s98, s98 clamp
	v_rcp_f32_e32 v202, v202
	v_rcp_f32_e32 v203, v203
	v_rcp_f32_e32 v204, v204
	v_rcp_f32_e32 v205, v205
	v_rcp_f32_e32 v206, v206
	v_rcp_f32_e32 v207, v207
	v_rcp_f32_e32 v208, v208
	v_rcp_f32_e32 v209, v209
	s_nop 0
	v_cvt_pk_u8_f32 v214, v202, 0, 0
	v_cvt_pk_u8_f32 v214, v203, 1, v214
	v_cvt_pk_u8_f32 v214, v206, 2, v214
	v_cvt_pk_u8_f32 v214, v207, 3, v214
	v_cvt_pk_u8_f32 v215, v204, 0, 0
	v_cvt_pk_u8_f32 v215, v205, 1, v215
	v_cvt_pk_u8_f32 v215, v208, 2, v215
	v_cvt_pk_u8_f32 v215, v209, 3, v215
	v_mad_i64_i32 v[186:187], s[42:43], v22, s62, v[28:29]
; __device__ __forceinline__ float sigmoidf_(float x) { return frcp(1.0f + fexp(-x)); }
;     __device__ __forceinline__ void operator()(const Acc& acc, const Unit& u, int wr, int wc, int fr, int fq) const {
;     ...
; #pragma unroll
;         for (int ai = 0; ai < 2; ++ai)
; #pragma unroll
;             for (int m = 0; m < 4; ++m) { const int row = row0 + ai * HALF + m * 16; const float rs = rsv[ai][m]; unsigned char* rowp = GT + (size_t)row * NGT + colt;
; #pragma unroll
;                 for (int bj = 0; bj < 2; ++bj) { f32x4 v0 = acc[ai][bj][m][0] * rs + bv[bj][0], v1 = acc[ai][bj][m][1] * rs + bv[bj][1];
;                     unsigned q0[4], q1[4];
; #pragma unroll
;                     for (int e = 0; e < 4; ++e) { q0[e] = (unsigned)fmaxf(sigmoidf_(v0[e]) * 255.0f + 0.5f, 1.0f); q1[e] = (unsigned)fmaxf(sigmoidf_(v1[e]) * 255.0f + 0.5f, 1.0f); }
;                     u32x2 w; w.x = q0[0] | (q0[1] << 8) | (q0[2] << 16) | (q0[3] << 24); w.y = q1[0] | (q1[1] << 8) | (q1[2] << 16) | (q1[3] << 24);
;                     *(u32x2*)(rowp + bj * HALF) = w; } }
	v_lshl_add_u64 v[186:187], v[186:187], 0, v[26:27]
	global_store_dwordx2 v[186:187], v[214:215], off
	v_fma_f32 v202, v134, v200, v6
	v_fma_f32 v203, v135, v200, v7
	v_fma_f32 v204, v130, v200, v2
	v_fma_f32 v205, v131, v200, v3
	v_fma_f32 v206, v136, v200, v8
	v_fma_f32 v207, v137, v200, v9
	v_fma_f32 v208, v132, v200, v4
	v_fma_f32 v209, v133, v200, v5
	v_exp_f32_e32 v202, v202
	v_exp_f32_e32 v203, v203
	v_exp_f32_e32 v204, v204
	v_exp_f32_e32 v205, v205
	v_exp_f32_e32 v206, v206
	v_exp_f32_e32 v207, v207
	v_exp_f32_e32 v208, v208
	v_exp_f32_e32 v209, v209
	s_nop 0
	v_fma_f32 v202, v202, s98, s98 clamp
	v_fma_f32 v203, v203, s98, s98 clamp
	v_fma_f32 v204, v204, s98, s98 clamp
	v_fma_f32 v205, v205, s98, s98 clamp
	v_fma_f32 v206, v206, s98, s98 clamp
	v_fma_f32 v207, v207, s98, s98 clamp
	v_fma_f32 v208, v208, s98, s98 clamp
	v_fma_f32 v209, v209, s98, s98 clamp
	v_rcp_f32_e32 v202, v202
	v_rcp_f32_e32 v203, v203
	v_rcp_f32_e32 v204, v204
	v_rcp_f32_e32 v205, v205
	v_rcp_f32_e32 v206, v206
	v_rcp_f32_e32 v207, v207
	v_rcp_f32_e32 v208, v208
	v_rcp_f32_e32 v209, v209
	s_nop 0
	v_cvt_pk_u8_f32 v216, v202, 0, 0
	v_cvt_pk_u8_f32 v216, v203, 1, v216
	v_cvt_pk_u8_f32 v216, v206, 2, v216
	v_cvt_pk_u8_f32 v216, v207, 3, v216
	v_cvt_pk_u8_f32 v217, v204, 0, 0
	v_cvt_pk_u8_f32 v217, v205, 1, v217
	v_cvt_pk_u8_f32 v217, v208, 2, v217
	v_cvt_pk_u8_f32 v217, v209, 3, v217
	global_store_dwordx2 v[186:187], v[216:217], off offset:128
	v_fma_f32 v202, v126, v184, v14
	v_fma_f32 v203, v127, v184, v15
	v_fma_f32 v204, v122, v184, v10
	v_fma_f32 v205, v123, v184, v11
	v_fma_f32 v206, v128, v184, v16
	v_fma_f32 v207, v129, v184, v17
	v_fma_f32 v208, v124, v184, v12
	v_fma_f32 v209, v125, v184, v13
	v_exp_f32_e32 v202, v202
	v_exp_f32_e32 v203, v203
	v_exp_f32_e32 v204, v204
	v_exp_f32_e32 v205, v205
	v_exp_f32_e32 v206, v206
	v_exp_f32_e32 v207, v207
	v_exp_f32_e32 v208, v208
	v_exp_f32_e32 v209, v209
	s_nop 0
	v_fma_f32 v202, v202, s98, s98 clamp
	v_fma_f32 v203, v203, s98, s98 clamp
	v_fma_f32 v204, v204, s98, s98 clamp
	v_fma_f32 v205, v205, s98, s98 clamp
	v_fma_f32 v206, v206, s98, s98 clamp
	v_fma_f32 v207, v207, s98, s98 clamp
	v_fma_f32 v208, v208, s98, s98 clamp
	v_fma_f32 v209, v209, s98, s98 clamp
	v_rcp_f32_e32 v202, v202
	v_rcp_f32_e32 v203, v203
	v_rcp_f32_e32 v204, v204
	v_rcp_f32_e32 v205, v205
	v_rcp_f32_e32 v206, v206
	v_rcp_f32_e32 v207, v207
	v_rcp_f32_e32 v208, v208
	v_rcp_f32_e32 v209, v209
	s_nop 0
	v_cvt_pk_u8_f32 v210, v202, 0, 0
	v_cvt_pk_u8_f32 v210, v203, 1, v210
	v_cvt_pk_u8_f32 v210, v206, 2, v210
	v_cvt_pk_u8_f32 v210, v207, 3, v210
	v_cvt_pk_u8_f32 v211, v204, 0, 0
	v_cvt_pk_u8_f32 v211, v205, 1, v211
	v_cvt_pk_u8_f32 v211, v208, 2, v211
	v_cvt_pk_u8_f32 v211, v209, 3, v211
	v_mad_i64_i32 v[186:187], s[42:43], v20, s62, v[28:29]
	v_lshl_add_u64 v[186:187], v[186:187], 0, v[26:27]
	global_store_dwordx2 v[186:187], v[210:211], off
	v_fma_f32 v202, v118, v184, v6
	v_fma_f32 v203, v114, v184, v2
	v_fma_f32 v204, v119, v184, v7
	v_fma_f32 v205, v115, v184, v3
	v_fma_f32 v206, v120, v184, v8
	v_fma_f32 v207, v116, v184, v4
	v_fma_f32 v208, v121, v184, v9
	v_fma_f32 v209, v117, v184, v5
	v_exp_f32_e32 v202, v202
	v_exp_f32_e32 v203, v203
	v_exp_f32_e32 v204, v204
	v_exp_f32_e32 v205, v205
	v_exp_f32_e32 v206, v206
	v_exp_f32_e32 v207, v207
	v_exp_f32_e32 v208, v208
	v_exp_f32_e32 v209, v209
	s_nop 0
	v_fma_f32 v202, v202, s98, s98 clamp
	v_fma_f32 v203, v203, s98, s98 clamp
	v_fma_f32 v204, v204, s98, s98 clamp
	v_fma_f32 v205, v205, s98, s98 clamp
	v_fma_f32 v206, v206, s98, s98 clamp
	v_fma_f32 v207, v207, s98, s98 clamp
	v_fma_f32 v208, v208, s98, s98 clamp
	v_fma_f32 v209, v209, s98, s98 clamp
	v_rcp_f32_e32 v202, v202
	v_rcp_f32_e32 v203, v203
	v_rcp_f32_e32 v204, v204
	v_rcp_f32_e32 v205, v205
	v_rcp_f32_e32 v206, v206
	v_rcp_f32_e32 v207, v207
	v_rcp_f32_e32 v208, v208
	v_rcp_f32_e32 v209, v209
	s_nop 0
	v_cvt_pk_u8_f32 v212, v202, 0, 0
	v_cvt_pk_u8_f32 v212, v204, 1, v212
	v_cvt_pk_u8_f32 v212, v206, 2, v212
	v_cvt_pk_u8_f32 v212, v208, 3, v212
	v_cvt_pk_u8_f32 v213, v203, 0, 0
	v_cvt_pk_u8_f32 v213, v205, 1, v213
	v_cvt_pk_u8_f32 v213, v207, 2, v213
	v_cvt_pk_u8_f32 v213, v209, 3, v213
	global_store_dwordx2 v[186:187], v[212:213], off offset:128
	v_fma_f32 v202, v106, v170, v10
	v_fma_f32 v203, v107, v170, v11
	v_fma_f32 v204, v110, v170, v14
	v_fma_f32 v205, v111, v170, v15
	v_fma_f32 v206, v112, v170, v16
	v_fma_f32 v207, v108, v170, v12
	v_fma_f32 v208, v113, v170, v17
	v_fma_f32 v209, v109, v170, v13
	v_exp_f32_e32 v202, v202
	v_exp_f32_e32 v203, v203
	v_exp_f32_e32 v204, v204
	v_exp_f32_e32 v205, v205
	v_exp_f32_e32 v206, v206
	v_exp_f32_e32 v207, v207
	v_exp_f32_e32 v208, v208
	v_exp_f32_e32 v209, v209
	s_nop 0
	v_fma_f32 v202, v202, s98, s98 clamp
	v_fma_f32 v203, v203, s98, s98 clamp
	v_fma_f32 v204, v204, s98, s98 clamp
	v_fma_f32 v205, v205, s98, s98 clamp
	v_fma_f32 v206, v206, s98, s98 clamp
	v_fma_f32 v207, v207, s98, s98 clamp
	v_fma_f32 v208, v208, s98, s98 clamp
	v_fma_f32 v209, v209, s98, s98 clamp
	v_rcp_f32_e32 v202, v202
	v_rcp_f32_e32 v203, v203
	v_rcp_f32_e32 v204, v204
	v_rcp_f32_e32 v205, v205
	v_rcp_f32_e32 v206, v206
	v_rcp_f32_e32 v207, v207
	v_rcp_f32_e32 v208, v208
	v_rcp_f32_e32 v209, v209
	s_nop 0
	v_cvt_pk_u8_f32 v214, v204, 0, 0
	v_cvt_pk_u8_f32 v214, v205, 1, v214
	v_cvt_pk_u8_f32 v214, v206, 2, v214
	v_cvt_pk_u8_f32 v214, v208, 3, v214
	v_cvt_pk_u8_f32 v215, v202, 0, 0
	v_cvt_pk_u8_f32 v215, v203, 1, v215
	v_cvt_pk_u8_f32 v215, v207, 2, v215
	v_cvt_pk_u8_f32 v215, v209, 3, v215
	v_mad_i64_i32 v[184:185], s[42:43], v18, s62, v[28:29]
	v_lshl_add_u64 v[184:185], v[184:185], 0, v[26:27]
; __device__ __forceinline__ float sigmoidf_(float x) { return frcp(1.0f + fexp(-x)); }
;     __device__ __forceinline__ void operator()(const Acc& acc, const Unit& u, int wr, int wc, int fr, int fq) const {
;     ...
; #pragma unroll
;         for (int ai = 0; ai < 2; ++ai)
; #pragma unroll
;             for (int m = 0; m < 4; ++m) { const int row = row0 + ai * HALF + m * 16; const float rs = rsv[ai][m]; unsigned char* rowp = GT + (size_t)row * NGT + colt;
; #pragma unroll
;                 for (int bj = 0; bj < 2; ++bj) { f32x4 v0 = acc[ai][bj][m][0] * rs + bv[bj][0], v1 = acc[ai][bj][m][1] * rs + bv[bj][1];
;                     unsigned q0[4], q1[4];
; #pragma unroll
;                     for (int e = 0; e < 4; ++e) { q0[e] = (unsigned)fmaxf(sigmoidf_(v0[e]) * 255.0f + 0.5f, 1.0f); q1[e] = (unsigned)fmaxf(sigmoidf_(v1[e]) * 255.0f + 0.5f, 1.0f); }
;                     u32x2 w; w.x = q0[0] | (q0[1] << 8) | (q0[2] << 16) | (q0[3] << 24); w.y = q1[0] | (q1[1] << 8) | (q1[2] << 16) | (q1[3] << 24);
;                     *(u32x2*)(rowp + bj * HALF) = w; } }
	global_store_dwordx2 v[184:185], v[214:215], off
	v_fma_f32 v202, v98, v170, v2
	v_fma_f32 v203, v99, v170, v3
	v_fma_f32 v204, v102, v170, v6
	v_fma_f32 v205, v100, v170, v4
	v_fma_f32 v206, v103, v170, v7
	v_fma_f32 v207, v104, v170, v8
	v_fma_f32 v208, v105, v170, v9
	v_fma_f32 v209, v101, v170, v5
	v_exp_f32_e32 v202, v202
	v_exp_f32_e32 v203, v203
	v_exp_f32_e32 v204, v204
	v_exp_f32_e32 v205, v205
	v_exp_f32_e32 v206, v206
	v_exp_f32_e32 v207, v207
	v_exp_f32_e32 v208, v208
	v_exp_f32_e32 v209, v209
	s_nop 0
	v_fma_f32 v202, v202, s98, s98 clamp
	v_fma_f32 v203, v203, s98, s98 clamp
	v_fma_f32 v204, v204, s98, s98 clamp
	v_fma_f32 v205, v205, s98, s98 clamp
	v_fma_f32 v206, v206, s98, s98 clamp
	v_fma_f32 v207, v207, s98, s98 clamp
	v_fma_f32 v208, v208, s98, s98 clamp
	v_fma_f32 v209, v209, s98, s98 clamp
	v_rcp_f32_e32 v202, v202
	v_rcp_f32_e32 v203, v203
	v_rcp_f32_e32 v204, v204
	v_rcp_f32_e32 v205, v205
	v_rcp_f32_e32 v206, v206
	v_rcp_f32_e32 v207, v207
	v_rcp_f32_e32 v208, v208
	v_rcp_f32_e32 v209, v209
	s_nop 0
	v_cvt_pk_u8_f32 v216, v204, 0, 0
	v_cvt_pk_u8_f32 v216, v206, 1, v216
	v_cvt_pk_u8_f32 v216, v207, 2, v216
	v_cvt_pk_u8_f32 v216, v208, 3, v216
	v_cvt_pk_u8_f32 v217, v202, 0, 0
	v_cvt_pk_u8_f32 v217, v203, 1, v217
	v_cvt_pk_u8_f32 v217, v205, 2, v217
	v_cvt_pk_u8_f32 v217, v209, 3, v217
	global_store_dwordx2 v[184:185], v[216:217], off offset:128
	v_fma_f32 v202, v90, v33, v10
	v_fma_f32 v203, v91, v33, v11
	v_fma_f32 v204, v92, v33, v12
	v_fma_f32 v205, v94, v33, v14
	v_fma_f32 v206, v95, v33, v15
	v_fma_f32 v207, v96, v33, v16
	v_fma_f32 v208, v97, v33, v17
	v_fma_f32 v209, v93, v33, v13
	v_exp_f32_e32 v202, v202
	v_exp_f32_e32 v203, v203
	v_exp_f32_e32 v204, v204
	v_exp_f32_e32 v205, v205
	v_exp_f32_e32 v206, v206
	v_exp_f32_e32 v207, v207
	v_exp_f32_e32 v208, v208
	v_exp_f32_e32 v209, v209
	s_nop 0
	v_fma_f32 v202, v202, s98, s98 clamp
	v_fma_f32 v203, v203, s98, s98 clamp
	v_fma_f32 v204, v204, s98, s98 clamp
	v_fma_f32 v205, v205, s98, s98 clamp
	v_fma_f32 v206, v206, s98, s98 clamp
	v_fma_f32 v207, v207, s98, s98 clamp
	v_fma_f32 v208, v208, s98, s98 clamp
	v_fma_f32 v209, v209, s98, s98 clamp
	v_rcp_f32_e32 v202, v202
	v_rcp_f32_e32 v203, v203
	v_rcp_f32_e32 v204, v204
	v_rcp_f32_e32 v205, v205
	v_rcp_f32_e32 v206, v206
	v_rcp_f32_e32 v207, v207
	v_rcp_f32_e32 v208, v208
	v_rcp_f32_e32 v209, v209
	s_nop 0
	v_cvt_pk_u8_f32 v210, v205, 0, 0
	v_cvt_pk_u8_f32 v210, v206, 1, v210
	v_cvt_pk_u8_f32 v210, v207, 2, v210
	v_cvt_pk_u8_f32 v210, v208, 3, v210
	v_cvt_pk_u8_f32 v211, v202, 0, 0
	v_cvt_pk_u8_f32 v211, v203, 1, v211
	v_cvt_pk_u8_f32 v211, v204, 2, v211
	v_cvt_pk_u8_f32 v211, v209, 3, v211
	v_mad_i64_i32 v[184:185], s[42:43], v183, s62, v[28:29]
	v_lshl_add_u64 v[184:185], v[184:185], 0, v[26:27]
	global_store_dwordx2 v[184:185], v[210:211], off
	v_fma_f32 v202, v82, v33, v2
	v_fma_f32 v203, v83, v33, v3
	v_fma_f32 v204, v84, v33, v4
	v_fma_f32 v205, v86, v33, v6
	v_fma_f32 v206, v87, v33, v7
	v_fma_f32 v207, v88, v33, v8
	v_fma_f32 v208, v89, v33, v9
	v_fma_f32 v209, v85, v33, v5
	v_exp_f32_e32 v202, v202
	v_exp_f32_e32 v203, v203
	v_exp_f32_e32 v204, v204
	v_exp_f32_e32 v205, v205
	v_exp_f32_e32 v206, v206
	v_exp_f32_e32 v207, v207
	v_exp_f32_e32 v208, v208
	v_exp_f32_e32 v209, v209
	s_nop 0
	v_fma_f32 v202, v202, s98, s98 clamp
	v_fma_f32 v203, v203, s98, s98 clamp
	v_fma_f32 v204, v204, s98, s98 clamp
	v_fma_f32 v205, v205, s98, s98 clamp
	v_fma_f32 v206, v206, s98, s98 clamp
	v_fma_f32 v207, v207, s98, s98 clamp
	v_fma_f32 v208, v208, s98, s98 clamp
	v_fma_f32 v209, v209, s98, s98 clamp
	v_rcp_f32_e32 v202, v202
	v_rcp_f32_e32 v203, v203
	v_rcp_f32_e32 v204, v204
	v_rcp_f32_e32 v205, v205
	v_rcp_f32_e32 v206, v206
	v_rcp_f32_e32 v207, v207
	v_rcp_f32_e32 v208, v208
	v_rcp_f32_e32 v209, v209
	s_nop 0
	v_cvt_pk_u8_f32 v212, v205, 0, 0
	v_cvt_pk_u8_f32 v212, v206, 1, v212
	v_cvt_pk_u8_f32 v212, v207, 2, v212
	v_cvt_pk_u8_f32 v212, v208, 3, v212
	v_cvt_pk_u8_f32 v213, v202, 0, 0
	v_cvt_pk_u8_f32 v213, v203, 1, v213
	v_cvt_pk_u8_f32 v213, v204, 2, v213
	v_cvt_pk_u8_f32 v213, v209, 3, v213
	global_store_dwordx2 v[184:185], v[212:213], off offset:128
	v_fma_f32 v202, v78, v32, v14
	v_fma_f32 v203, v79, v32, v15
	v_fma_f32 v204, v74, v32, v10
	v_fma_f32 v205, v75, v32, v11
	v_fma_f32 v206, v80, v32, v16
	v_fma_f32 v207, v81, v32, v17
	v_fma_f32 v208, v76, v32, v12
	v_fma_f32 v209, v77, v32, v13
	v_exp_f32_e32 v202, v202
	v_exp_f32_e32 v203, v203
	v_exp_f32_e32 v204, v204
	v_exp_f32_e32 v205, v205
	v_exp_f32_e32 v206, v206
	v_exp_f32_e32 v207, v207
	v_exp_f32_e32 v208, v208
	v_exp_f32_e32 v209, v209
	s_nop 0
	v_fma_f32 v202, v202, s98, s98 clamp
	v_fma_f32 v203, v203, s98, s98 clamp
	v_fma_f32 v204, v204, s98, s98 clamp
	v_fma_f32 v205, v205, s98, s98 clamp
	v_fma_f32 v206, v206, s98, s98 clamp
	v_fma_f32 v207, v207, s98, s98 clamp
	v_fma_f32 v208, v208, s98, s98 clamp
	v_fma_f32 v209, v209, s98, s98 clamp
	v_rcp_f32_e32 v202, v202
	v_rcp_f32_e32 v203, v203
	v_rcp_f32_e32 v204, v204
	v_rcp_f32_e32 v205, v205
	v_rcp_f32_e32 v206, v206
	v_rcp_f32_e32 v207, v207
	v_rcp_f32_e32 v208, v208
	v_rcp_f32_e32 v209, v209
	s_nop 0
	v_cvt_pk_u8_f32 v214, v202, 0, 0
	v_cvt_pk_u8_f32 v214, v203, 1, v214
	v_cvt_pk_u8_f32 v214, v206, 2, v214
	v_cvt_pk_u8_f32 v214, v207, 3, v214
	v_cvt_pk_u8_f32 v215, v204, 0, 0
	v_cvt_pk_u8_f32 v215, v205, 1, v215
	v_cvt_pk_u8_f32 v215, v208, 2, v215
	v_cvt_pk_u8_f32 v215, v209, 3, v215
	v_mad_i64_i32 v[184:185], s[42:43], v182, s62, v[28:29]
	v_lshl_add_u64 v[184:185], v[184:185], 0, v[26:27]
	global_store_dwordx2 v[184:185], v[214:215], off
	v_fma_f32 v202, v70, v32, v6
	v_fma_f32 v203, v66, v32, v2
; __device__ __forceinline__ float sigmoidf_(float x) { return frcp(1.0f + fexp(-x)); }
;     __device__ __forceinline__ void operator()(const Acc& acc, const Unit& u, int wr, int wc, int fr, int fq) const {
;     ...
; #pragma unroll
;         for (int ai = 0; ai < 2; ++ai)
; #pragma unroll
;             for (int m = 0; m < 4; ++m) { const int row = row0 + ai * HALF + m * 16; const float rs = rsv[ai][m]; unsigned char* rowp = GT + (size_t)row * NGT + colt;
; #pragma unroll
;                 for (int bj = 0; bj < 2; ++bj) { f32x4 v0 = acc[ai][bj][m][0] * rs + bv[bj][0], v1 = acc[ai][bj][m][1] * rs + bv[bj][1];
;                     unsigned q0[4], q1[4];
; #pragma unroll
;                     for (int e = 0; e < 4; ++e) { q0[e] = (unsigned)fmaxf(sigmoidf_(v0[e]) * 255.0f + 0.5f, 1.0f); q1[e] = (unsigned)fmaxf(sigmoidf_(v1[e]) * 255.0f + 0.5f, 1.0f); }
;                     u32x2 w; w.x = q0[0] | (q0[1] << 8) | (q0[2] << 16) | (q0[3] << 24); w.y = q1[0] | (q1[1] << 8) | (q1[2] << 16) | (q1[3] << 24);
;                     *(u32x2*)(rowp + bj * HALF) = w; } }
	v_fma_f32 v204, v71, v32, v7
	v_fma_f32 v205, v67, v32, v3
	v_fma_f32 v206, v72, v32, v8
	v_fma_f32 v207, v68, v32, v4
	v_fma_f32 v208, v73, v32, v9
	v_fma_f32 v209, v69, v32, v5
	v_exp_f32_e32 v202, v202
	v_exp_f32_e32 v203, v203
	v_exp_f32_e32 v204, v204
	v_exp_f32_e32 v205, v205
	v_exp_f32_e32 v206, v206
	v_exp_f32_e32 v207, v207
	v_exp_f32_e32 v208, v208
	v_exp_f32_e32 v209, v209
	s_nop 0
	v_fma_f32 v202, v202, s98, s98 clamp
	v_fma_f32 v203, v203, s98, s98 clamp
	v_fma_f32 v204, v204, s98, s98 clamp
	v_fma_f32 v205, v205, s98, s98 clamp
	v_fma_f32 v206, v206, s98, s98 clamp
	v_fma_f32 v207, v207, s98, s98 clamp
	v_fma_f32 v208, v208, s98, s98 clamp
	v_fma_f32 v209, v209, s98, s98 clamp
	v_rcp_f32_e32 v202, v202
	v_rcp_f32_e32 v203, v203
	v_rcp_f32_e32 v204, v204
	v_rcp_f32_e32 v205, v205
	v_rcp_f32_e32 v206, v206
	v_rcp_f32_e32 v207, v207
	v_rcp_f32_e32 v208, v208
	v_rcp_f32_e32 v209, v209
	s_nop 0
	v_cvt_pk_u8_f32 v216, v202, 0, 0
	v_cvt_pk_u8_f32 v216, v204, 1, v216
	v_cvt_pk_u8_f32 v216, v206, 2, v216
	v_cvt_pk_u8_f32 v216, v208, 3, v216
	v_cvt_pk_u8_f32 v217, v203, 0, 0
	v_cvt_pk_u8_f32 v217, v205, 1, v217
	v_cvt_pk_u8_f32 v217, v207, 2, v217
	v_cvt_pk_u8_f32 v217, v209, 3, v217
	global_store_dwordx2 v[184:185], v[216:217], off offset:128
	v_mad_i64_i32 v[32:33], s[42:43], v181, s62, v[28:29]
	v_fma_f32 v202, v58, v31, v10
	v_fma_f32 v203, v59, v31, v11
	v_fma_f32 v204, v63, v31, v15
	v_fma_f32 v205, v60, v31, v12
	v_fma_f32 v206, v62, v31, v14
	v_fma_f32 v207, v64, v31, v16
	v_fma_f32 v208, v65, v31, v17
	v_fma_f32 v209, v61, v31, v13
	v_exp_f32_e32 v202, v202
	v_exp_f32_e32 v203, v203
	v_exp_f32_e32 v204, v204
	v_exp_f32_e32 v205, v205
	v_exp_f32_e32 v206, v206
	v_exp_f32_e32 v207, v207
	v_exp_f32_e32 v208, v208
	v_exp_f32_e32 v209, v209
	s_nop 0
	v_fma_f32 v202, v202, s98, s98 clamp
	v_fma_f32 v203, v203, s98, s98 clamp
	v_fma_f32 v204, v204, s98, s98 clamp
	v_fma_f32 v205, v205, s98, s98 clamp
	v_fma_f32 v206, v206, s98, s98 clamp
	v_fma_f32 v207, v207, s98, s98 clamp
	v_fma_f32 v208, v208, s98, s98 clamp
	v_fma_f32 v209, v209, s98, s98 clamp
	v_rcp_f32_e32 v202, v202
	v_rcp_f32_e32 v203, v203
	v_rcp_f32_e32 v204, v204
	v_rcp_f32_e32 v205, v205
	v_rcp_f32_e32 v206, v206
	v_rcp_f32_e32 v207, v207
	v_rcp_f32_e32 v208, v208
	v_rcp_f32_e32 v209, v209
	s_nop 0
	v_cvt_pk_u8_f32 v210, v206, 0, 0
	v_cvt_pk_u8_f32 v210, v204, 1, v210
	v_cvt_pk_u8_f32 v210, v207, 2, v210
	v_cvt_pk_u8_f32 v210, v208, 3, v210
	v_cvt_pk_u8_f32 v211, v202, 0, 0
	v_cvt_pk_u8_f32 v211, v203, 1, v211
	v_cvt_pk_u8_f32 v211, v205, 2, v211
	v_cvt_pk_u8_f32 v211, v209, 3, v211
	v_mad_i64_i32 v[28:29], s[42:43], v180, s62, v[28:29]
	v_lshl_add_u64 v[32:33], v[32:33], 0, v[26:27]
	v_lshl_add_u64 v[26:27], v[28:29], 0, v[26:27]
	v_fma_f32 v202, v42, v30, v10
	v_fma_f32 v203, v47, v30, v15
	v_fma_f32 v204, v43, v30, v11
	v_fma_f32 v205, v48, v30, v16
	v_fma_f32 v206, v44, v30, v12
	v_fma_f32 v207, v46, v30, v14
	v_fma_f32 v208, v49, v30, v17
	v_fma_f32 v209, v45, v30, v13
	v_exp_f32_e32 v202, v202
	v_exp_f32_e32 v203, v203
	v_exp_f32_e32 v204, v204
	v_exp_f32_e32 v205, v205
	v_exp_f32_e32 v206, v206
	v_exp_f32_e32 v207, v207
	v_exp_f32_e32 v208, v208
	v_exp_f32_e32 v209, v209
	s_nop 0
	v_fma_f32 v202, v202, s98, s98 clamp
	v_fma_f32 v203, v203, s98, s98 clamp
	v_fma_f32 v204, v204, s98, s98 clamp
	v_fma_f32 v205, v205, s98, s98 clamp
	v_fma_f32 v206, v206, s98, s98 clamp
	v_fma_f32 v207, v207, s98, s98 clamp
	v_fma_f32 v208, v208, s98, s98 clamp
	v_fma_f32 v209, v209, s98, s98 clamp
	v_rcp_f32_e32 v202, v202
	v_rcp_f32_e32 v203, v203
	v_rcp_f32_e32 v204, v204
	v_rcp_f32_e32 v205, v205
	v_rcp_f32_e32 v206, v206
	v_rcp_f32_e32 v207, v207
	v_rcp_f32_e32 v208, v208
	v_rcp_f32_e32 v209, v209
	s_nop 0
	v_cvt_pk_u8_f32 v212, v207, 0, 0
	v_cvt_pk_u8_f32 v212, v203, 1, v212
	v_cvt_pk_u8_f32 v212, v205, 2, v212
	v_cvt_pk_u8_f32 v212, v208, 3, v212
	v_cvt_pk_u8_f32 v213, v202, 0, 0
	v_cvt_pk_u8_f32 v213, v204, 1, v213
	v_cvt_pk_u8_f32 v213, v206, 2, v213
	v_cvt_pk_u8_f32 v213, v209, 3, v213
	global_store_dwordx2 v[32:33], v[210:211], off
	global_store_dwordx2 v[26:27], v[212:213], off
	v_fma_f32 v202, v50, v31, v2
	v_fma_f32 v203, v55, v31, v7
	v_fma_f32 v204, v51, v31, v3
	v_fma_f32 v205, v52, v31, v4
	v_fma_f32 v206, v54, v31, v6
	v_fma_f32 v207, v56, v31, v8
	v_fma_f32 v208, v57, v31, v9
	v_fma_f32 v209, v53, v31, v5
	v_exp_f32_e32 v202, v202
	v_exp_f32_e32 v203, v203
	v_exp_f32_e32 v204, v204
	v_exp_f32_e32 v205, v205
	v_exp_f32_e32 v206, v206
	v_exp_f32_e32 v207, v207
	v_exp_f32_e32 v208, v208
	v_exp_f32_e32 v209, v209
	s_nop 0
	v_fma_f32 v202, v202, s98, s98 clamp
	v_fma_f32 v203, v203, s98, s98 clamp
	v_fma_f32 v204, v204, s98, s98 clamp
	v_fma_f32 v205, v205, s98, s98 clamp
	v_fma_f32 v206, v206, s98, s98 clamp
	v_fma_f32 v207, v207, s98, s98 clamp
	v_fma_f32 v208, v208, s98, s98 clamp
	v_fma_f32 v209, v209, s98, s98 clamp
	v_rcp_f32_e32 v202, v202
	v_rcp_f32_e32 v203, v203
	v_rcp_f32_e32 v204, v204
	v_rcp_f32_e32 v205, v205
	v_rcp_f32_e32 v206, v206
	v_rcp_f32_e32 v207, v207
	v_rcp_f32_e32 v208, v208
	v_rcp_f32_e32 v209, v209
	s_nop 0
	v_cvt_pk_u8_f32 v214, v206, 0, 0
	v_cvt_pk_u8_f32 v214, v203, 1, v214
	v_cvt_pk_u8_f32 v214, v207, 2, v214
	v_cvt_pk_u8_f32 v214, v208, 3, v214
	v_cvt_pk_u8_f32 v215, v202, 0, 0
	v_cvt_pk_u8_f32 v215, v204, 1, v215
	v_cvt_pk_u8_f32 v215, v205, 2, v215
	v_cvt_pk_u8_f32 v215, v209, 3, v215
	v_fma_f32 v202, v34, v30, v2
	v_fma_f32 v203, v39, v30, v7
	v_fma_f32 v204, v35, v30, v3
	v_fma_f32 v205, v40, v30, v8
	v_fma_f32 v206, v36, v30, v4
	v_fma_f32 v207, v38, v30, v6
	v_fma_f32 v208, v41, v30, v9
	v_fma_f32 v209, v37, v30, v5
	v_exp_f32_e32 v202, v202
	v_exp_f32_e32 v203, v203
	v_exp_f32_e32 v204, v204
	v_exp_f32_e32 v205, v205
	v_exp_f32_e32 v206, v206
	v_exp_f32_e32 v207, v207
	v_exp_f32_e32 v208, v208
	v_exp_f32_e32 v209, v209
	s_nop 0
	v_fma_f32 v202, v202, s98, s98 clamp
	v_fma_f32 v203, v203, s98, s98 clamp
	v_fma_f32 v204, v204, s98, s98 clamp
	v_fma_f32 v205, v205, s98, s98 clamp
	v_fma_f32 v206, v206, s98, s98 clamp
	v_fma_f32 v207, v207, s98, s98 clamp
	v_fma_f32 v208, v208, s98, s98 clamp
	v_fma_f32 v209, v209, s98, s98 clamp
	v_rcp_f32_e32 v202, v202
	v_rcp_f32_e32 v203, v203
	v_rcp_f32_e32 v204, v204
	v_rcp_f32_e32 v205, v205
	v_rcp_f32_e32 v206, v206
	v_rcp_f32_e32 v207, v207
	v_rcp_f32_e32 v208, v208
	v_rcp_f32_e32 v209, v209
	s_nop 0
	v_cvt_pk_u8_f32 v216, v207, 0, 0
	v_cvt_pk_u8_f32 v216, v203, 1, v216
	v_cvt_pk_u8_f32 v216, v205, 2, v216
	v_cvt_pk_u8_f32 v216, v208, 3, v216
	v_cvt_pk_u8_f32 v217, v202, 0, 0
	v_cvt_pk_u8_f32 v217, v204, 1, v217
	v_cvt_pk_u8_f32 v217, v206, 2, v217
	v_cvt_pk_u8_f32 v217, v209, 3, v217
	global_store_dwordx2 v[32:33], v[214:215], off offset:128
	global_store_dwordx2 v[26:27], v[216:217], off offset:128
	s_cbranch_execz .LBB0_574
